# P3: odd-vcu CUs run their attention units first and the sample-attention/spatial-gate units after (memory-bound small units overlap other CUs' attention)
# baseline (speedup 1.0000x reference)
; #define LAS __attribute__((address_space(3)))
; #define FRESH() const int lane = fresh_lane(); const int tid = wave * 64 + lane; (void)tid
; #define REPS(k) _Pragma("nounroll") for (int rep_ = 0, nrep_ = opaque_i(((PROBE_REP >> (k)) & 1) ? 2 : 1); rep_ < nrep_; ++rep_)
; __device__ __forceinline__ void sattn_unit(const Args& a, LAS unsigned char* lds, const LAS float* bt, int db, int h, int t, int tid, int wave, int lane) {
;     asm volatile("" : "+v"(lane), "+v"(tid));
;     const int qg = wave & 1, dvh = (wave >> 1) & 1, ksp = wave >> 2, hi = lane >> 5, r32 = lane & 31;
;     const bf16* Qb = (const bf16*)(a.ws + WS_Q); const bf16* Kb = (const bf16*)(a.ws + WS_K); const bf16* Vb = (const bf16*)(a.ws + WS_V); bf16* Ob = (bf16*)(a.ws + WS_O);
;     const float* CK = a.in[I_CK]; const float* CV = a.in[I_CV];
;     const LAS float* bth = bt + h * 196;
;     bf16x8 qr[4];
;     { const bf16* qp = Qb + (size_t)(MP + db * 64 + qg * 32 + r32) * 1024 + h * 128 + t * 64 + hi * 8;
; #pragma unroll
;       for (int d0 = 0; d0 < 4; ++d0) qr[d0] = *(const bf16x8*)(qp + d0 * 16); }
;     float m = -1e30f, l = 0.f; f32x16 o[2];
;     o[0] = f32x16{}; o[1] = f32x16{};
;     const unsigned klo = (unsigned)(r32 * 1024 + hi * 8), vlo = (unsigned)(hi * 4096 + dvh * 64 + r32), kco = (unsigned)((lane >> 4) * 1024 + (lane & 15) * 4);
;     LAS float* kst = (LAS float*)(lds + 40960 + wave * 8704);
;     f32x4 kr[8]; float vr[2][16];
; __global__ void __launch_bounds__(NTHR, 2) fwd_megakernel(Args args) {
;     ...
;         LAS float* bt = (LAS float*)(lds + BT_OFF);
;         __syncthreads();
;         { FRESH(); bias_table(args, bt, tid); }
;         __syncthreads();
;         REPS(10) for (int v = vcu; v < 256; v += G) {
;     ...
;             { FRESH(); sattn_unit(args, lds, bt, v >> 4, (v >> 1) & 7, v & 1, tid, wave, lane); }
;             { FRESH(); sgate_unit(args, lds, v, tid, wave, lane); } if (v >= 240) { FRESH(); sgate_unit(args, lds, 256 + (v - 240), tid, wave, lane); }
;     ...
;         }
.LBB0_289:
	s_or_b64 exec, exec, s[4:5]
	s_mov_b32 s0, 1
	s_waitcnt lgkmcnt(0)
	s_barrier
	s_cmp_lt_i32 s0, 1
	v_writelane_b32 v251, s0, 43
	v_writelane_b32 v251, s75, 40
	s_cbranch_scc1 .LBB0_365
	v_readlane_b32 s0, v251, 9
	s_mov_b32 s1, 0
	s_bitcmp1_b32 s0, 0
	v_writelane_b32 v251, s1, 62
	s_cbranch_scc0 .Lp3_small_entry
	s_mov_b32 s1, 1
	s_nop 0
	v_writelane_b32 v251, s1, 62
	v_writelane_b32 v251, s11, 50
	v_writelane_b32 v251, s22, 51
	v_writelane_b32 v251, s23, 52
	v_writelane_b32 v251, s40, 53
	v_writelane_b32 v251, s41, 54
	v_writelane_b32 v251, s42, 55
	v_writelane_b32 v251, s43, 56
	v_writelane_b32 v251, s52, 57
	v_writelane_b32 v251, s53, 58
	v_writelane_b32 v251, s54, 59
	v_writelane_b32 v251, s55, 60
	v_writelane_b32 v251, s56, 61
	v_writelane_b32 v251, s57, 63
	s_branch .LBB0_365
.Lp3_small_second:
	s_mov_b64 exec, -1
	s_mov_b32 s1, 2
	s_nop 0
	v_writelane_b32 v251, s1, 62
	s_nop 1
	v_readlane_b32 s11, v251, 50
	v_readlane_b32 s22, v251, 51
	v_readlane_b32 s23, v251, 52
	v_readlane_b32 s40, v251, 53
	v_readlane_b32 s41, v251, 54
	v_readlane_b32 s42, v251, 55
	v_readlane_b32 s43, v251, 56
	v_readlane_b32 s52, v251, 57
	v_readlane_b32 s53, v251, 58
	v_readlane_b32 s54, v251, 59
	v_readlane_b32 s55, v251, 60
	v_readlane_b32 s56, v251, 61
	v_readlane_b32 s57, v251, 63
	s_nop 4
.Lp3_small_entry:
	v_readlane_b32 s0, v251, 9
	s_cmpk_lt_i32 s0, 0x100
	s_cselect_b64 s[0:1], -1, 0
	v_writelane_b32 v251, s0, 44
	v_mbcnt_lo_u32_b32 v0, -1, 0
	v_mbcnt_hi_u32_b32 v189, -1, v0
	v_writelane_b32 v251, s1, 45
	s_add_u32 s0, s68, 0x1ec00000
	s_addc_u32 s1, s69, 0
	v_writelane_b32 v251, s0, 36
	s_add_u32 s5, s68, 0x27000000
	v_and_b32_e32 v191, 64, v189
	v_writelane_b32 v251, s1, 37
	s_addc_u32 s0, s69, 0
	v_writelane_b32 v251, s0, 32
	s_lshr_b32 s4, s30, 8
	v_readlane_b32 s2, v251, 10
	s_lshl_b32 s0, s2, 5
	s_and_b32 s85, s0, 32
	s_add_u32 s1, s68, 0x2b200000
	v_writelane_b32 v251, s1, 22
	s_addc_u32 s1, s69, 0
	s_and_b32 s91, s0, 64
	v_writelane_b32 v251, s1, 24
	s_mul_i32 s0, s2, 0x2200
	s_add_u32 s1, s68, 0x22e00000
	v_writelane_b32 v251, s1, 26
	s_addc_u32 s1, s69, 0
	s_add_i32 s94, s0, 0
	s_cmpk_lt_u32 s30, 0x100
	s_cselect_b64 s[24:25], -1, 0
	v_writelane_b32 v251, s1, 28
	s_and_b64 s[0:1], s[24:25], exec
	s_cselect_b32 s97, 33, 31
	s_or_b32 s10, s85, 0x786
	s_cmp_eq_u32 s4, 1
	s_cselect_b64 s[26:27], -1, 0
	s_bfe_u32 s0, s30, 0x20006
	s_lshl_b32 s1, s0, 13
	s_add_i32 s3, s1, 0
	s_mul_i32 s1, s0, 0xffffe200
	v_writelane_b32 v251, s3, 30
	s_add_i32 s1, s3, s1
	v_writelane_b32 v251, s1, 11
	s_lshl_b32 s1, s2, 13
	s_sub_i32 s3, s94, s1
	s_add_u32 s28, s68, 0x1aa00000
	s_addc_u32 s29, s69, 0
	s_add_u32 s44, s68, 0x16800000
	s_addc_u32 s45, s69, 0
	s_add_u32 s46, s68, 0xe400000
	s_addc_u32 s47, s69, 0
	s_lshl_b32 s13, s2, 4
	s_cmpk_lt_u32 s30, 0x200
	v_writelane_b32 v251, s3, 14
	s_cselect_b64 s[8:9], -1, 0
	v_writelane_b32 v251, s8, 20
	s_lshl_b32 s12, s2, 7
	s_or_b32 s2, s13, 4
	v_writelane_b32 v251, s9, 21
	v_writelane_b32 v251, s2, 16
	s_lshl_b32 s2, s2, 3
	v_writelane_b32 v251, s2, 46
	s_or_b32 s2, s13, 8
	v_writelane_b32 v251, s2, 18
	s_lshl_b32 s2, s2, 3
	v_writelane_b32 v251, s2, 47
	s_or_b32 s2, s13, 12
	s_mov_b32 s3, s2
	s_lshl_b32 s2, s2, 3
	v_writelane_b32 v251, s2, 48
	s_lshl_b32 s2, s0, 5
	s_cmp_gt_u32 s0, 1
	s_mul_i32 s95, s4, 0x420
	s_mul_i32 s96, s4, 33
	s_cselect_b64 s[50:51], -1, 0
	s_lshl_b32 s8, s4, 6
	s_lshl_b32 s4, s4, 14
	v_readlane_b32 s76, v251, 0
	s_mov_b32 s9, s13
	s_add_i32 s13, s4, 0
	v_readlane_b32 s82, v251, 6
	v_readlane_b32 s83, v251, 7
	s_cmp_lt_u32 s0, 2
	s_mov_b64 s[6:7], s[82:83]
	s_cselect_b64 s[74:75], -1, 0
	v_readlane_b32 s77, v251, 1
	v_readlane_b32 s80, v251, 4
	s_add_u32 s76, s6, 0x21000000
	s_mov_b32 s21, 0
	s_mov_b32 s82, s5
	s_addc_u32 s77, s7, 0
	s_add_i32 s0, s1, 0
	v_mov_b32_e32 v113, 0
	s_mov_b32 s31, 0xf149f2ca
	s_mov_b32 s83, 0x5040100
	s_movk_i32 s84, 0x7fff
	s_mov_b32 s86, 0x3a800000
	s_mov_b32 s87, 0xf800000
	v_mov_b32_e32 v188, 0x260
	v_xor_b32_e32 v190, 32, v189
	v_add_u32_e32 v192, 64, v191
	v_mov_b32_e32 v193, 0xc0
	s_mov_b32 s80, 0
	v_readlane_b32 s78, v251, 2
	v_readlane_b32 s79, v251, 3
	v_readlane_b32 s81, v251, 5
	v_writelane_b32 v251, s0, 49
	s_branch .LBB0_292

; #define FRESH() const int lane = fresh_lane(); const int tid = wave * 64 + lane; (void)tid
; #define REPS(k) _Pragma("nounroll") for (int rep_ = 0, nrep_ = opaque_i(((PROBE_REP >> (k)) & 1) ? 2 : 1); rep_ < nrep_; ++rep_)
; __global__ void __launch_bounds__(NTHR, 2) fwd_megakernel(Args args) {
;     ...
;         REPS(10) for (int v = vcu; v < 256; v += G) {
;     ...
;             { FRESH(); sattn_unit(args, lds, bt, v >> 4, (v >> 1) & 7, v & 1, tid, wave, lane); }
;             { FRESH(); sgate_unit(args, lds, v, tid, wave, lane); } if (v >= 240) { FRESH(); sgate_unit(args, lds, 256 + (v - 240), tid, wave, lane); }
;     ...
;         }
;         __syncthreads();
;         REPS(11) for (int v = vcu; v < 256; v += G) {
.LBB0_364:
	v_readlane_b32 s80, v251, 34
	s_mov_b32 s92, s80
	v_readlane_b32 s30, v251, 13
	v_readlane_b32 s75, v251, 40
	v_readlane_b32 s81, v251, 35
	v_readlane_b32 s0, v251, 62
	s_cmp_eq_u32 s0, 2
	s_cbranch_scc1 .LBB0_450

; #define REPS(k) _Pragma("nounroll") for (int rep_ = 0, nrep_ = opaque_i(((PROBE_REP >> (k)) & 1) ? 2 : 1); rep_ < nrep_; ++rep_)
; __global__ void __launch_bounds__(NTHR, 2) fwd_megakernel(Args args) {
;     ...
;         REPS(11) for (int v = vcu; v < 256; v += G) {
;             const int combo = v >> 3, j = v & 7; const int b = combo >> 4, hh = combo & 15;
; #pragma nounroll
;             for (int i = 0; i < 8; ++i) { const int x = 8 * (i >> 1) + j; int qb = (i & 1) ? 63 - x : x; int b_ = b, hh_ = hh; asm volatile("" : "+s"(qb), "+s"(b_), "+s"(hh_));
;     ...
;                 attn_body::attn_unit<8>(b_, hh_, qb, (const attn_body::bf16*)(ws + WS_Q), (const attn_body::bf16*)(ws + WS_K), (const attn_body::bf16*)(ws + WS_V), (attn_body::bf16*)(ws + WS_O), (char*)lds_raw, (attn_body::lds_cfptr)(bt + (hh_ >> 1) * 196), wave);
;     ...
;             }
;         }
;     }
.LBB0_449:
	v_readlane_b32 s80, v251, 34
	s_mov_b32 s92, s80
	v_readlane_b32 s30, v251, 13
	v_readlane_b32 s75, v251, 40
	v_readlane_b32 s81, v251, 35
	v_readlane_b32 s0, v251, 62
	s_cmp_eq_u32 s0, 1
	s_cbranch_scc1 .Lp3_small_second
